# down-GEMM residual epilogue: gate and base-row loads issued up front behind counted waits instead of a load-wait-store round trip per step
# baseline (speedup 1.0000x reference)
.LBB0_1223:
	s_ashr_i32 s11, s38, 3
	s_mul_hi_i32 s18, s11, 0xc000
	s_mul_i32 s11, s11, 0xc000
	s_add_u32 s11, s40, s11
	s_addc_u32 s22, s41, s18
	s_lshl_b32 s18, s39, 8
	s_ashr_i32 s19, s18, 31
	s_lshl_b64 s[20:21], s[18:19], 2
	s_add_u32 s20, s11, s20
	s_addc_u32 s21, s22, s21
	s_lshl_b32 s22, s38, 8
	s_ashr_i32 s23, s22, 31
	s_lshl_b64 s[22:23], s[22:23], 11
	s_add_u32 s18, s22, s18
	s_addc_u32 s19, s23, s19
	v_mov_b32_e32 v0, v147
	v_mov_b32_e32 v142, v146
	s_lshl_b64 s[18:19], s[18:19], 1
	s_add_u32 s38, s36, s18
	v_lshl_add_u32 v144, v142, 3, s49
	v_lshl_add_u32 v150, v0, 11, s56
	v_add_u32_e32 v0, v144, v150
	s_addc_u32 s39, s37, s19
	v_ashrrev_i32_e32 v145, 31, v144
	v_lshlrev_b64 v[160:161], 1, v[0:1]
	v_lshl_add_u64 v[142:143], v[144:145], 2, s[20:21]
	v_lshl_add_u64 v[168:169], s[38:39], 0, v[160:161]
	s_add_u32 s18, s46, s18
	s_addc_u32 s19, s47, s19
	s_andn2_b64 vcc, exec, s[12:13]
	v_lshlrev_b32_e32 v0, 1, v0
	global_load_dwordx4 v[150:153], v[142:143], off
	global_load_dwordx4 v[154:157], v[142:143], off offset:16
	global_load_dwordx4 v[158:161], v[142:143], off offset:512
	global_load_dwordx4 v[196:199], v[142:143], off offset:528
	s_add_u32 s98, s38, 0x0
	s_addc_u32 s99, s39, 0
	global_load_dwordx4 v[168:171], v0, s[98:99]
	global_load_dwordx4 v[172:175], v0, s[98:99] offset:256
	s_add_u32 s98, s38, 0x10000
	s_addc_u32 s99, s39, 0
	global_load_dwordx4 v[176:179], v0, s[98:99]
	global_load_dwordx4 v[182:185], v0, s[98:99] offset:256
	s_add_u32 s98, s38, 0x20000
	s_addc_u32 s99, s39, 0
	global_load_dwordx4 v[186:189], v0, s[98:99]
	global_load_dwordx4 v[190:193], v0, s[98:99] offset:256
	s_add_u32 s98, s38, 0x30000
	s_addc_u32 s99, s39, 0
	global_load_dwordx4 v[204:207], v0, s[98:99]
	global_load_dwordx4 v[208:211], v0, s[98:99] offset:256
	s_add_u32 s98, s38, 0x80000
	s_addc_u32 s99, s39, 0
	global_load_dwordx4 v[216:219], v0, s[98:99]
	global_load_dwordx4 v[220:223], v0, s[98:99] offset:256
	s_waitcnt vmcnt(9)
	v_lshlrev_b32_e32 v226, 16, v168
	v_and_b32_e32 v227, 0xffff0000, v168
	v_lshlrev_b32_e32 v228, 16, v169
	v_and_b32_e32 v229, 0xffff0000, v169
	v_lshlrev_b32_e32 v230, 16, v170
	v_and_b32_e32 v231, 0xffff0000, v170
	v_lshlrev_b32_e32 v232, 16, v171
	v_and_b32_e32 v233, 0xffff0000, v171
	v_pk_fma_f32 v[126:127], v[126:127], v[150:151], v[226:227]
	v_pk_fma_f32 v[128:129], v[128:129], v[152:153], v[228:229]
	v_pk_fma_f32 v[122:123], v[122:123], v[154:155], v[230:231]
	v_pk_fma_f32 v[124:125], v[124:125], v[156:157], v[232:233]
	v_cvt_pk_bf16_f32 v126, v126, v127
	v_cvt_pk_bf16_f32 v127, v128, v129
	v_cvt_pk_bf16_f32 v128, v122, v123
	v_cvt_pk_bf16_f32 v129, v124, v125
	s_add_u32 s100, s18, 0x0
	s_addc_u32 s101, s19, 0
	global_store_dwordx4 v0, v[126:129], s[100:101]
	s_add_u32 s98, s38, 0x90000
	s_addc_u32 s99, s39, 0
	global_load_dwordx4 v[122:125], v0, s[98:99]
	s_waitcnt vmcnt(10)
	v_lshlrev_b32_e32 v226, 16, v172
	v_and_b32_e32 v227, 0xffff0000, v172
	v_lshlrev_b32_e32 v228, 16, v173
	v_and_b32_e32 v229, 0xffff0000, v173
	v_lshlrev_b32_e32 v230, 16, v174
	v_and_b32_e32 v231, 0xffff0000, v174
	v_lshlrev_b32_e32 v232, 16, v175
	v_and_b32_e32 v233, 0xffff0000, v175
	v_pk_fma_f32 v[118:119], v[118:119], v[158:159], v[226:227]
	v_pk_fma_f32 v[120:121], v[120:121], v[160:161], v[228:229]
	v_pk_fma_f32 v[114:115], v[114:115], v[196:197], v[230:231]
	v_pk_fma_f32 v[116:117], v[116:117], v[198:199], v[232:233]
	v_cvt_pk_bf16_f32 v118, v118, v119
	v_cvt_pk_bf16_f32 v119, v120, v121
	v_cvt_pk_bf16_f32 v120, v114, v115
	v_cvt_pk_bf16_f32 v121, v116, v117
	global_store_dwordx4 v0, v[118:121], s[100:101] offset:256
	s_add_u32 s98, s38, 0x90000
	s_addc_u32 s99, s39, 0
	global_load_dwordx4 v[114:117], v0, s[98:99] offset:256
	s_waitcnt vmcnt(11)
	v_lshlrev_b32_e32 v226, 16, v176
	v_and_b32_e32 v227, 0xffff0000, v176
	v_lshlrev_b32_e32 v228, 16, v177
	v_and_b32_e32 v229, 0xffff0000, v177
	v_lshlrev_b32_e32 v230, 16, v178
	v_and_b32_e32 v231, 0xffff0000, v178
	v_lshlrev_b32_e32 v232, 16, v179
	v_and_b32_e32 v233, 0xffff0000, v179
	v_pk_fma_f32 v[110:111], v[110:111], v[150:151], v[226:227]
	v_pk_fma_f32 v[112:113], v[112:113], v[152:153], v[228:229]
	v_pk_fma_f32 v[106:107], v[106:107], v[154:155], v[230:231]
	v_pk_fma_f32 v[108:109], v[108:109], v[156:157], v[232:233]
	v_cvt_pk_bf16_f32 v110, v110, v111
	v_cvt_pk_bf16_f32 v111, v112, v113
	v_cvt_pk_bf16_f32 v112, v106, v107
	v_cvt_pk_bf16_f32 v113, v108, v109
	s_add_u32 s100, s18, 0x10000
	s_addc_u32 s101, s19, 0
	global_store_dwordx4 v0, v[110:113], s[100:101]
	s_add_u32 s98, s38, 0xa0000
	s_addc_u32 s99, s39, 0
	global_load_dwordx4 v[106:109], v0, s[98:99]
	s_waitcnt vmcnt(12)
	v_lshlrev_b32_e32 v226, 16, v182
	v_and_b32_e32 v227, 0xffff0000, v182
	v_lshlrev_b32_e32 v228, 16, v183
	v_and_b32_e32 v229, 0xffff0000, v183
	v_lshlrev_b32_e32 v230, 16, v184
	v_and_b32_e32 v231, 0xffff0000, v184
	v_lshlrev_b32_e32 v232, 16, v185
	v_and_b32_e32 v233, 0xffff0000, v185
	v_pk_fma_f32 v[102:103], v[102:103], v[158:159], v[226:227]
	v_pk_fma_f32 v[104:105], v[104:105], v[160:161], v[228:229]
	v_pk_fma_f32 v[98:99], v[98:99], v[196:197], v[230:231]
	v_pk_fma_f32 v[100:101], v[100:101], v[198:199], v[232:233]
	v_cvt_pk_bf16_f32 v102, v102, v103
	v_cvt_pk_bf16_f32 v103, v104, v105
	v_cvt_pk_bf16_f32 v104, v98, v99
	v_cvt_pk_bf16_f32 v105, v100, v101
	global_store_dwordx4 v0, v[102:105], s[100:101] offset:256
	s_add_u32 s98, s38, 0xa0000
	s_addc_u32 s99, s39, 0
	global_load_dwordx4 v[98:101], v0, s[98:99] offset:256
	s_waitcnt vmcnt(13)
	v_lshlrev_b32_e32 v226, 16, v186
	v_and_b32_e32 v227, 0xffff0000, v186
	v_lshlrev_b32_e32 v228, 16, v187
	v_and_b32_e32 v229, 0xffff0000, v187
	v_lshlrev_b32_e32 v230, 16, v188
	v_and_b32_e32 v231, 0xffff0000, v188
	v_lshlrev_b32_e32 v232, 16, v189
	v_and_b32_e32 v233, 0xffff0000, v189
	v_pk_fma_f32 v[94:95], v[94:95], v[150:151], v[226:227]
	v_pk_fma_f32 v[96:97], v[96:97], v[152:153], v[228:229]
	v_pk_fma_f32 v[90:91], v[90:91], v[154:155], v[230:231]
	v_pk_fma_f32 v[92:93], v[92:93], v[156:157], v[232:233]
	v_cvt_pk_bf16_f32 v94, v94, v95
	v_cvt_pk_bf16_f32 v95, v96, v97
	v_cvt_pk_bf16_f32 v96, v90, v91
	v_cvt_pk_bf16_f32 v97, v92, v93
	s_add_u32 s100, s18, 0x20000
	s_addc_u32 s101, s19, 0
	global_store_dwordx4 v0, v[94:97], s[100:101]
	s_add_u32 s98, s38, 0xb0000
	s_addc_u32 s99, s39, 0
	global_load_dwordx4 v[90:93], v0, s[98:99]
	s_waitcnt vmcnt(14)
	v_lshlrev_b32_e32 v226, 16, v190
	v_and_b32_e32 v227, 0xffff0000, v190
	v_lshlrev_b32_e32 v228, 16, v191
	v_and_b32_e32 v229, 0xffff0000, v191
	v_lshlrev_b32_e32 v230, 16, v192
	v_and_b32_e32 v231, 0xffff0000, v192
	v_lshlrev_b32_e32 v232, 16, v193
	v_and_b32_e32 v233, 0xffff0000, v193
	v_pk_fma_f32 v[86:87], v[86:87], v[158:159], v[226:227]
	v_pk_fma_f32 v[88:89], v[88:89], v[160:161], v[228:229]
	v_pk_fma_f32 v[82:83], v[82:83], v[196:197], v[230:231]
	v_pk_fma_f32 v[84:85], v[84:85], v[198:199], v[232:233]
	v_cvt_pk_bf16_f32 v86, v86, v87
	v_cvt_pk_bf16_f32 v87, v88, v89
	v_cvt_pk_bf16_f32 v88, v82, v83
	v_cvt_pk_bf16_f32 v89, v84, v85
	global_store_dwordx4 v0, v[86:89], s[100:101] offset:256
	s_add_u32 s98, s38, 0xb0000
	s_addc_u32 s99, s39, 0
	global_load_dwordx4 v[82:85], v0, s[98:99] offset:256
	s_waitcnt vmcnt(15)
	v_lshlrev_b32_e32 v226, 16, v204
	v_and_b32_e32 v227, 0xffff0000, v204
	v_lshlrev_b32_e32 v228, 16, v205
	v_and_b32_e32 v229, 0xffff0000, v205
	v_lshlrev_b32_e32 v230, 16, v206
	v_and_b32_e32 v231, 0xffff0000, v206
	v_lshlrev_b32_e32 v232, 16, v207
	v_and_b32_e32 v233, 0xffff0000, v207
	v_pk_fma_f32 v[78:79], v[78:79], v[150:151], v[226:227]
	v_pk_fma_f32 v[80:81], v[80:81], v[152:153], v[228:229]
	v_pk_fma_f32 v[74:75], v[74:75], v[154:155], v[230:231]
	v_pk_fma_f32 v[76:77], v[76:77], v[156:157], v[232:233]
	v_cvt_pk_bf16_f32 v78, v78, v79
	v_cvt_pk_bf16_f32 v79, v80, v81
	v_cvt_pk_bf16_f32 v80, v74, v75
	v_cvt_pk_bf16_f32 v81, v76, v77
	s_add_u32 s100, s18, 0x30000
	s_addc_u32 s101, s19, 0
	global_store_dwordx4 v0, v[78:81], s[100:101]
	s_waitcnt vmcnt(15)
	v_lshlrev_b32_e32 v226, 16, v208
	v_and_b32_e32 v227, 0xffff0000, v208
	v_lshlrev_b32_e32 v228, 16, v209
	v_and_b32_e32 v229, 0xffff0000, v209
	v_lshlrev_b32_e32 v230, 16, v210
	v_and_b32_e32 v231, 0xffff0000, v210
	v_lshlrev_b32_e32 v232, 16, v211
	v_and_b32_e32 v233, 0xffff0000, v211
	v_pk_fma_f32 v[70:71], v[70:71], v[158:159], v[226:227]
	v_pk_fma_f32 v[72:73], v[72:73], v[160:161], v[228:229]
	v_pk_fma_f32 v[66:67], v[66:67], v[196:197], v[230:231]
	v_pk_fma_f32 v[68:69], v[68:69], v[198:199], v[232:233]
	v_cvt_pk_bf16_f32 v70, v70, v71
	v_cvt_pk_bf16_f32 v71, v72, v73
	v_cvt_pk_bf16_f32 v72, v66, v67
	v_cvt_pk_bf16_f32 v73, v68, v69
	global_store_dwordx4 v0, v[70:73], s[100:101] offset:256
	s_waitcnt vmcnt(15)
	v_lshlrev_b32_e32 v226, 16, v216
	v_and_b32_e32 v227, 0xffff0000, v216
	v_lshlrev_b32_e32 v228, 16, v217
	v_and_b32_e32 v229, 0xffff0000, v217
	v_lshlrev_b32_e32 v230, 16, v218
	v_and_b32_e32 v231, 0xffff0000, v218
	v_lshlrev_b32_e32 v232, 16, v219
	v_and_b32_e32 v233, 0xffff0000, v219
	v_pk_fma_f32 v[62:63], v[62:63], v[150:151], v[226:227]
	v_pk_fma_f32 v[64:65], v[64:65], v[152:153], v[228:229]
	v_pk_fma_f32 v[58:59], v[58:59], v[154:155], v[230:231]
	v_pk_fma_f32 v[60:61], v[60:61], v[156:157], v[232:233]
	v_cvt_pk_bf16_f32 v62, v62, v63
	v_cvt_pk_bf16_f32 v63, v64, v65
	v_cvt_pk_bf16_f32 v64, v58, v59
	v_cvt_pk_bf16_f32 v65, v60, v61
	s_add_u32 s100, s18, 0x80000
	s_addc_u32 s101, s19, 0
	global_store_dwordx4 v0, v[62:65], s[100:101]
	s_waitcnt vmcnt(15)
	v_lshlrev_b32_e32 v226, 16, v220
	v_and_b32_e32 v227, 0xffff0000, v220
	v_lshlrev_b32_e32 v228, 16, v221
	v_and_b32_e32 v229, 0xffff0000, v221
	v_lshlrev_b32_e32 v230, 16, v222
	v_and_b32_e32 v231, 0xffff0000, v222
	v_lshlrev_b32_e32 v232, 16, v223
	v_and_b32_e32 v233, 0xffff0000, v223
	v_pk_fma_f32 v[54:55], v[54:55], v[158:159], v[226:227]
	v_pk_fma_f32 v[56:57], v[56:57], v[160:161], v[228:229]
	v_pk_fma_f32 v[50:51], v[50:51], v[196:197], v[230:231]
	v_pk_fma_f32 v[52:53], v[52:53], v[198:199], v[232:233]
	v_cvt_pk_bf16_f32 v54, v54, v55
	v_cvt_pk_bf16_f32 v55, v56, v57
	v_cvt_pk_bf16_f32 v56, v50, v51
	v_cvt_pk_bf16_f32 v57, v52, v53
	global_store_dwordx4 v0, v[54:57], s[100:101] offset:256
	s_waitcnt vmcnt(14)
	v_lshlrev_b32_e32 v226, 16, v122
	v_and_b32_e32 v227, 0xffff0000, v122
	v_lshlrev_b32_e32 v228, 16, v123
	v_and_b32_e32 v229, 0xffff0000, v123
	v_lshlrev_b32_e32 v230, 16, v124
	v_and_b32_e32 v231, 0xffff0000, v124
	v_lshlrev_b32_e32 v232, 16, v125
	v_and_b32_e32 v233, 0xffff0000, v125
	v_pk_fma_f32 v[46:47], v[46:47], v[150:151], v[226:227]
	v_pk_fma_f32 v[48:49], v[48:49], v[152:153], v[228:229]
	v_pk_fma_f32 v[42:43], v[42:43], v[154:155], v[230:231]
	v_pk_fma_f32 v[44:45], v[44:45], v[156:157], v[232:233]
	v_cvt_pk_bf16_f32 v46, v46, v47
	v_cvt_pk_bf16_f32 v47, v48, v49
	v_cvt_pk_bf16_f32 v48, v42, v43
	v_cvt_pk_bf16_f32 v49, v44, v45
	s_add_u32 s100, s18, 0x90000
	s_addc_u32 s101, s19, 0
	global_store_dwordx4 v0, v[46:49], s[100:101]
	s_waitcnt vmcnt(13)
	v_lshlrev_b32_e32 v226, 16, v114
	v_and_b32_e32 v227, 0xffff0000, v114
	v_lshlrev_b32_e32 v228, 16, v115
	v_and_b32_e32 v229, 0xffff0000, v115
	v_lshlrev_b32_e32 v230, 16, v116
	v_and_b32_e32 v231, 0xffff0000, v116
	v_lshlrev_b32_e32 v232, 16, v117
	v_and_b32_e32 v233, 0xffff0000, v117
	v_pk_fma_f32 v[38:39], v[38:39], v[158:159], v[226:227]
	v_pk_fma_f32 v[40:41], v[40:41], v[160:161], v[228:229]
	v_pk_fma_f32 v[34:35], v[34:35], v[196:197], v[230:231]
	v_pk_fma_f32 v[36:37], v[36:37], v[198:199], v[232:233]
	v_cvt_pk_bf16_f32 v38, v38, v39
	v_cvt_pk_bf16_f32 v39, v40, v41
	v_cvt_pk_bf16_f32 v40, v34, v35
	v_cvt_pk_bf16_f32 v41, v36, v37
	global_store_dwordx4 v0, v[38:41], s[100:101] offset:256
	s_waitcnt vmcnt(12)
	v_lshlrev_b32_e32 v226, 16, v106
	v_and_b32_e32 v227, 0xffff0000, v106
	v_lshlrev_b32_e32 v228, 16, v107
	v_and_b32_e32 v229, 0xffff0000, v107
	v_lshlrev_b32_e32 v230, 16, v108
	v_and_b32_e32 v231, 0xffff0000, v108
	v_lshlrev_b32_e32 v232, 16, v109
	v_and_b32_e32 v233, 0xffff0000, v109
	v_pk_fma_f32 v[30:31], v[30:31], v[150:151], v[226:227]
	v_pk_fma_f32 v[32:33], v[32:33], v[152:153], v[228:229]
	v_pk_fma_f32 v[26:27], v[26:27], v[154:155], v[230:231]
	v_pk_fma_f32 v[28:29], v[28:29], v[156:157], v[232:233]
	v_cvt_pk_bf16_f32 v30, v30, v31
	v_cvt_pk_bf16_f32 v31, v32, v33
	v_cvt_pk_bf16_f32 v32, v26, v27
	v_cvt_pk_bf16_f32 v33, v28, v29
	s_add_u32 s100, s18, 0xa0000
	s_addc_u32 s101, s19, 0
	global_store_dwordx4 v0, v[30:33], s[100:101]
	s_waitcnt vmcnt(11)
	v_lshlrev_b32_e32 v226, 16, v98
	v_and_b32_e32 v227, 0xffff0000, v98
	v_lshlrev_b32_e32 v228, 16, v99
	v_and_b32_e32 v229, 0xffff0000, v99
	v_lshlrev_b32_e32 v230, 16, v100
	v_and_b32_e32 v231, 0xffff0000, v100
	v_lshlrev_b32_e32 v232, 16, v101
	v_and_b32_e32 v233, 0xffff0000, v101
	v_pk_fma_f32 v[22:23], v[22:23], v[158:159], v[226:227]
	v_pk_fma_f32 v[24:25], v[24:25], v[160:161], v[228:229]
	v_pk_fma_f32 v[18:19], v[18:19], v[196:197], v[230:231]
	v_pk_fma_f32 v[20:21], v[20:21], v[198:199], v[232:233]
	v_cvt_pk_bf16_f32 v22, v22, v23
	v_cvt_pk_bf16_f32 v23, v24, v25
	v_cvt_pk_bf16_f32 v24, v18, v19
	v_cvt_pk_bf16_f32 v25, v20, v21
	global_store_dwordx4 v0, v[22:25], s[100:101] offset:256
	s_waitcnt vmcnt(10)
	v_lshlrev_b32_e32 v226, 16, v90
	v_and_b32_e32 v227, 0xffff0000, v90
	v_lshlrev_b32_e32 v228, 16, v91
	v_and_b32_e32 v229, 0xffff0000, v91
	v_lshlrev_b32_e32 v230, 16, v92
	v_and_b32_e32 v231, 0xffff0000, v92
	v_lshlrev_b32_e32 v232, 16, v93
	v_and_b32_e32 v233, 0xffff0000, v93
	v_pk_fma_f32 v[14:15], v[14:15], v[150:151], v[226:227]
	v_pk_fma_f32 v[16:17], v[16:17], v[152:153], v[228:229]
	v_pk_fma_f32 v[10:11], v[10:11], v[154:155], v[230:231]
	v_pk_fma_f32 v[12:13], v[12:13], v[156:157], v[232:233]
	v_cvt_pk_bf16_f32 v14, v14, v15
	v_cvt_pk_bf16_f32 v15, v16, v17
	v_cvt_pk_bf16_f32 v16, v10, v11
	v_cvt_pk_bf16_f32 v17, v12, v13
	s_add_u32 s100, s18, 0xb0000
	s_addc_u32 s101, s19, 0
	global_store_dwordx4 v0, v[14:17], s[100:101]
	s_waitcnt vmcnt(9)
	v_lshlrev_b32_e32 v226, 16, v82
	v_and_b32_e32 v227, 0xffff0000, v82
	v_lshlrev_b32_e32 v228, 16, v83
	v_and_b32_e32 v229, 0xffff0000, v83
	v_lshlrev_b32_e32 v230, 16, v84
	v_and_b32_e32 v231, 0xffff0000, v84
	v_lshlrev_b32_e32 v232, 16, v85
	v_and_b32_e32 v233, 0xffff0000, v85
	v_pk_fma_f32 v[6:7], v[6:7], v[158:159], v[226:227]
	v_pk_fma_f32 v[8:9], v[8:9], v[160:161], v[228:229]
	v_pk_fma_f32 v[2:3], v[2:3], v[196:197], v[230:231]
	v_pk_fma_f32 v[4:5], v[4:5], v[198:199], v[232:233]
	v_cvt_pk_bf16_f32 v6, v6, v7
	v_cvt_pk_bf16_f32 v7, v8, v9
	v_cvt_pk_bf16_f32 v8, v2, v3
	v_cvt_pk_bf16_f32 v9, v4, v5
	global_store_dwordx4 v0, v[6:9], s[100:101] offset:256
	s_mov_b64 s[18:19], -1
	s_cbranch_vccnz .LBB0_1212
	s_andn2_b64 vcc, exec, s[4:5]
	s_cbranch_vccnz .LBB0_1211
	s_barrier
	s_branch .LBB0_1211
